# per-item load chains de-serialised: A map-1 epilogue gain loads and C prologue rope-table loads issued up front
# baseline (speedup 1.0000x reference)
;     DI void* gp(int i) const { return (void*)(__attribute__((address_space(1))) void*)ld(i); }
; DI unsigned cvtpk(float lo, float hi) { unsigned r; asm volatile("v_cvt_pk_bf16_f32 %0, %1, %2" : "=v"(r) : "v"(lo), "v"(hi)); return r; }
; DI float bflo(unsigned w) { return __uint_as_float(w << 16); }
; DI float bfhi(unsigned w) { return __uint_as_float(w & 0xffff0000u); }
; template <int M> DI float sx(float v) { return __int_as_float(__builtin_amdgcn_ds_swizzle(__float_as_int(v), (M << 10) | 0x1f)); }
; template <int DQK, int MODE>
; DI void attn_body(const AttnArgs& a, char* lds) {
;     ...
;         } else {
;             float v[64]; float ss = 0.f;
; #pragma unroll
;             for (int c = 0; c < 8; ++c) { const u32x4 w2 = *(const u32x4*)(sp + c * 16); const u32x4 w1 = *(const u32x4*)(gp + c * 8);
;                 v[c * 8 + 0] = bflo(w1.x) - a.lam * bflo(w2.x); v[c * 8 + 1] = bfhi(w1.x) - a.lam * bfhi(w2.x);
;                 v[c * 8 + 2] = bflo(w1.y) - a.lam * bflo(w2.y); v[c * 8 + 3] = bfhi(w1.y) - a.lam * bfhi(w2.y);
;                 v[c * 8 + 4] = bflo(w1.z) - a.lam * bflo(w2.z); v[c * 8 + 5] = bfhi(w1.z) - a.lam * bfhi(w2.z);
;                 v[c * 8 + 6] = bflo(w1.w) - a.lam * bflo(w2.w); v[c * 8 + 7] = bfhi(w1.w) - a.lam * bfhi(w2.w); }
; #pragma unroll
;             for (int i = 0; i < 64; ++i) ss += v[i] * v[i];
;             ss += sx<1>(ss);
;             const float rn = rsqrtf(ss * (1.f / 128.f) + EPS) * a.oscale;
;             const float* gg = a.ga + hf * 64;
; #pragma unroll
;             for (int c = 0; c < 8; ++c) { const f32x4 g0 = *(const f32x4*)(gg + c * 8), g1 = *(const f32x4*)(gg + c * 8 + 4);
;                 u32x4 w; w.x = cvtpk(v[c * 8] * rn * g0[0], v[c * 8 + 1] * rn * g0[1]); w.y = cvtpk(v[c * 8 + 2] * rn * g0[2], v[c * 8 + 3] * rn * g0[3]);
;                 w.z = cvtpk(v[c * 8 + 4] * rn * g1[0], v[c * 8 + 5] * rn * g1[1]); w.w = cvtpk(v[c * 8 + 6] * rn * g1[2], v[c * 8 + 7] * rn * g1[3]);
;                 *(u32x4*)(gp + c * 8) = w; }
;         }
.LBB0_758:
	v_lshlrev_b32_e32 v60, 8, v6
	global_load_dwordx4 v[88:91], v60, s[60:61]
	global_load_dwordx4 v[92:95], v60, s[60:61] offset:16
	global_load_dwordx4 v[96:99], v60, s[60:61] offset:32
	global_load_dwordx4 v[100:103], v60, s[60:61] offset:48
	global_load_dwordx4 v[104:107], v60, s[60:61] offset:64
	global_load_dwordx4 v[108:111], v60, s[60:61] offset:80
	global_load_dwordx4 v[112:115], v60, s[60:61] offset:96
	global_load_dwordx4 v[116:119], v60, s[60:61] offset:112
	global_load_dwordx4 v[120:123], v60, s[60:61] offset:128
	global_load_dwordx4 v[124:127], v60, s[60:61] offset:144
	global_load_dwordx4 v[196:199], v60, s[60:61] offset:160
	global_load_dwordx4 v[200:203], v60, s[60:61] offset:176
	global_load_dwordx4 v[204:207], v60, s[60:61] offset:192
	global_load_dwordx4 v[208:211], v60, s[60:61] offset:208
	global_load_dwordx4 v[212:215], v60, s[60:61] offset:224
	global_load_dwordx4 v[216:219], v60, s[60:61] offset:240
	global_load_dwordx4 v[6:9], v[26:27], off offset:48
	global_load_dwordx4 v[14:17], v[26:27], off offset:32
	global_load_dwordx4 v[18:21], v[26:27], off offset:16
	global_load_dwordx4 v[10:13], v[26:27], off
	s_waitcnt lgkmcnt(0)
	v_lshlrev_b32_e32 v23, 16, v2
	s_waitcnt vmcnt(1)
	v_lshlrev_b32_e32 v28, 16, v18
	s_waitcnt vmcnt(0)
	v_lshlrev_b32_e32 v22, 16, v10
	v_fma_f32 v29, -v148, v23, v22
	v_and_b32_e32 v10, 0xffff0000, v10
	v_and_b32_e32 v22, 0xffff0000, v2
	v_fma_f32 v31, -v148, v22, v10
	v_lshlrev_b32_e32 v10, 16, v11
	v_lshlrev_b32_e32 v22, 16, v3
	v_fma_f32 v34, -v148, v22, v10
	v_and_b32_e32 v10, 0xffff0000, v11
	v_and_b32_e32 v11, 0xffff0000, v3
	v_fma_f32 v37, -v148, v11, v10
	v_lshlrev_b32_e32 v10, 16, v12
	v_lshlrev_b32_e32 v11, 16, v4
	v_fma_f32 v39, -v148, v11, v10
	v_and_b32_e32 v10, 0xffff0000, v12
	v_and_b32_e32 v11, 0xffff0000, v4
	v_fma_f32 v41, -v148, v11, v10
	v_lshlrev_b32_e32 v10, 16, v13
	v_lshlrev_b32_e32 v11, 16, v5
	v_fma_f32 v50, -v148, v11, v10
	v_and_b32_e32 v10, 0xffff0000, v13
	v_and_b32_e32 v11, 0xffff0000, v5
	v_fma_f32 v56, -v148, v11, v10
	ds_read_b128 v[22:25], v0 offset:16
	ds_read_b128 v[46:49], v0 offset:32
	ds_read_b128 v[62:65], v0 offset:48
	ds_read_b128 v[10:13], v0 offset:64
	v_and_b32_e32 v18, 0xffff0000, v18
	s_waitcnt lgkmcnt(3)
	v_lshlrev_b32_e32 v30, 16, v22
	v_and_b32_e32 v22, 0xffff0000, v22
	v_fma_f32 v52, -v148, v22, v18
	v_lshlrev_b32_e32 v18, 16, v19
	v_lshlrev_b32_e32 v22, 16, v23
	v_fma_f32 v53, -v148, v22, v18
	v_and_b32_e32 v18, 0xffff0000, v19
	v_and_b32_e32 v19, 0xffff0000, v23
	v_fma_f32 v54, -v148, v19, v18
	v_lshlrev_b32_e32 v18, 16, v20
	v_lshlrev_b32_e32 v19, 16, v24
	v_fma_f32 v55, -v148, v19, v18
	v_and_b32_e32 v18, 0xffff0000, v20
	v_and_b32_e32 v19, 0xffff0000, v24
	v_fma_f32 v57, -v148, v19, v18
	v_lshlrev_b32_e32 v18, 16, v21
	v_lshlrev_b32_e32 v19, 16, v25
	v_fma_f32 v58, -v148, v19, v18
	v_and_b32_e32 v18, 0xffff0000, v21
	v_and_b32_e32 v19, 0xffff0000, v25
	v_fma_f32 v59, -v148, v19, v18
	v_lshlrev_b32_e32 v18, 16, v14
	s_waitcnt lgkmcnt(2)
	v_lshlrev_b32_e32 v19, 16, v46
	v_fma_f32 v42, -v148, v19, v18
	v_and_b32_e32 v14, 0xffff0000, v14
	v_and_b32_e32 v18, 0xffff0000, v46
	v_fma_f32 v43, -v148, v18, v14
	v_lshlrev_b32_e32 v14, 16, v15
	v_lshlrev_b32_e32 v18, 16, v47
	v_fma_f32 v44, -v148, v18, v14
	v_and_b32_e32 v14, 0xffff0000, v15
	v_and_b32_e32 v15, 0xffff0000, v47
	v_fma_f32 v45, -v148, v15, v14
	v_lshlrev_b32_e32 v14, 16, v16
	v_lshlrev_b32_e32 v15, 16, v48
	v_fma_f32 v46, -v148, v15, v14
	v_and_b32_e32 v14, 0xffff0000, v16
	v_and_b32_e32 v15, 0xffff0000, v48
	v_fma_f32 v47, -v148, v15, v14
	v_lshlrev_b32_e32 v14, 16, v17
	v_lshlrev_b32_e32 v15, 16, v49
	v_fma_f32 v48, -v148, v15, v14
	v_and_b32_e32 v14, 0xffff0000, v17
	v_and_b32_e32 v15, 0xffff0000, v49
	v_fma_f32 v49, -v148, v15, v14
	v_lshlrev_b32_e32 v14, 16, v6
	s_waitcnt lgkmcnt(1)
	v_lshlrev_b32_e32 v15, 16, v62
	v_fma_f32 v40, -v148, v15, v14
	v_and_b32_e32 v6, 0xffff0000, v6
	v_and_b32_e32 v14, 0xffff0000, v62
	v_fma_f32 v38, -v148, v14, v6
	v_lshlrev_b32_e32 v6, 16, v7
	v_lshlrev_b32_e32 v14, 16, v63
	v_fma_f32 v36, -v148, v14, v6
	v_and_b32_e32 v6, 0xffff0000, v7
	v_and_b32_e32 v7, 0xffff0000, v63
	v_fma_f32 v35, -v148, v7, v6
	v_lshlrev_b32_e32 v6, 16, v8
	v_lshlrev_b32_e32 v7, 16, v64
	v_fma_f32 v33, -v148, v7, v6
	v_and_b32_e32 v6, 0xffff0000, v8
	v_and_b32_e32 v7, 0xffff0000, v64
	v_fma_f32 v32, -v148, v7, v6
	v_lshlrev_b32_e32 v6, 16, v9
	v_lshlrev_b32_e32 v7, 16, v65
	v_fma_f32 v51, -v148, v30, v28
	v_fma_f32 v30, -v148, v7, v6
	v_and_b32_e32 v6, 0xffff0000, v9
	v_and_b32_e32 v7, 0xffff0000, v65
	v_fma_f32 v28, -v148, v7, v6
	global_load_dwordx4 v[6:9], v[26:27], off offset:112
	global_load_dwordx4 v[14:17], v[26:27], off offset:96
	global_load_dwordx4 v[18:21], v[26:27], off offset:80
	global_load_dwordx4 v[22:25], v[26:27], off offset:64
	s_waitcnt lgkmcnt(0)
	v_lshlrev_b32_e32 v62, 16, v10
	v_and_b32_e32 v10, 0xffff0000, v10
	ds_read_b128 v[82:85], v0 offset:112
	s_waitcnt vmcnt(0)
	v_lshlrev_b32_e32 v61, 16, v22
	v_and_b32_e32 v22, 0xffff0000, v22
	v_fma_f32 v80, -v148, v10, v22
	v_lshlrev_b32_e32 v10, 16, v23
	v_lshlrev_b32_e32 v22, 16, v11
	v_fma_f32 v79, -v148, v22, v10
	v_and_b32_e32 v10, 0xffff0000, v23
	v_and_b32_e32 v11, 0xffff0000, v11
	v_fma_f32 v78, -v148, v11, v10
	v_lshlrev_b32_e32 v10, 16, v24
	v_lshlrev_b32_e32 v11, 16, v12
	v_fma_f32 v75, -v148, v11, v10
	v_and_b32_e32 v10, 0xffff0000, v24
	v_and_b32_e32 v11, 0xffff0000, v12
	v_fma_f32 v74, -v148, v11, v10
	v_lshlrev_b32_e32 v10, 16, v25
	v_lshlrev_b32_e32 v11, 16, v13
	v_fma_f32 v71, -v148, v11, v10
	v_and_b32_e32 v10, 0xffff0000, v25
	v_and_b32_e32 v11, 0xffff0000, v13
	v_fma_f32 v70, -v148, v11, v10
	ds_read_b128 v[10:13], v0 offset:80
	v_lshlrev_b32_e32 v22, 16, v18
	v_and_b32_e32 v18, 0xffff0000, v18
	v_fma_f32 v81, -v148, v62, v61
	s_waitcnt lgkmcnt(0)
;     DI void* gp(int i) const { return (void*)(__attribute__((address_space(1))) void*)ld(i); }
; DI unsigned cvtpk(float lo, float hi) { unsigned r; asm volatile("v_cvt_pk_bf16_f32 %0, %1, %2" : "=v"(r) : "v"(lo), "v"(hi)); return r; }
; template <int M> DI float sx(float v) { return __int_as_float(__builtin_amdgcn_ds_swizzle(__float_as_int(v), (M << 10) | 0x1f)); }
; template <int DQK, int MODE>
; DI void attn_body(const AttnArgs& a, char* lds) {
;     ...
; #pragma unroll
;             for (int i = 0; i < 64; ++i) ss += v[i] * v[i];
;             ss += sx<1>(ss);
;             const float rn = rsqrtf(ss * (1.f / 128.f) + EPS) * a.oscale;
;             const float* gg = a.ga + hf * 64;
; #pragma unroll
;             for (int c = 0; c < 8; ++c) { const f32x4 g0 = *(const f32x4*)(gg + c * 8), g1 = *(const f32x4*)(gg + c * 8 + 4);
;                 u32x4 w; w.x = cvtpk(v[c * 8] * rn * g0[0], v[c * 8 + 1] * rn * g0[1]); w.y = cvtpk(v[c * 8 + 2] * rn * g0[2], v[c * 8 + 3] * rn * g0[3]);
;                 w.z = cvtpk(v[c * 8 + 4] * rn * g1[0], v[c * 8 + 5] * rn * g1[1]); w.w = cvtpk(v[c * 8 + 6] * rn * g1[2], v[c * 8 + 7] * rn * g1[3]);
;                 *(u32x4*)(gp + c * 8) = w; }
	v_lshlrev_b32_e32 v23, 16, v10
	v_and_b32_e32 v10, 0xffff0000, v10
	v_fma_f32 v65, -v148, v10, v18
	v_lshlrev_b32_e32 v10, 16, v19
	v_lshlrev_b32_e32 v18, 16, v11
	v_fma_f32 v64, -v148, v18, v10
	v_and_b32_e32 v10, 0xffff0000, v19
	v_and_b32_e32 v11, 0xffff0000, v11
	v_fma_f32 v63, -v148, v11, v10
	v_lshlrev_b32_e32 v10, 16, v20
	v_lshlrev_b32_e32 v11, 16, v12
	v_fma_f32 v62, -v148, v11, v10
	v_and_b32_e32 v10, 0xffff0000, v20
	v_and_b32_e32 v11, 0xffff0000, v12
	v_fma_f32 v61, -v148, v11, v10
	v_lshlrev_b32_e32 v10, 16, v21
	v_lshlrev_b32_e32 v11, 16, v13
	v_fma_f32 v25, -v148, v11, v10
	v_and_b32_e32 v10, 0xffff0000, v21
	v_and_b32_e32 v11, 0xffff0000, v13
	v_fma_f32 v24, -v148, v11, v10
	ds_read_b128 v[10:13], v0 offset:96
	v_lshlrev_b32_e32 v18, 16, v14
	v_and_b32_e32 v14, 0xffff0000, v14
	v_fma_f32 v66, -v148, v23, v22
	s_waitcnt lgkmcnt(0)
	v_lshlrev_b32_e32 v19, 16, v10
	v_and_b32_e32 v10, 0xffff0000, v10
	v_fma_f32 v76, -v148, v10, v14
	v_lshlrev_b32_e32 v10, 16, v15
	v_lshlrev_b32_e32 v14, 16, v11
	v_fma_f32 v73, -v148, v14, v10
	v_mul_f32_e32 v14, v31, v31
	v_fmac_f32_e32 v14, v29, v29
	v_fmac_f32_e32 v14, v34, v34
	v_fmac_f32_e32 v14, v37, v37
	v_fmac_f32_e32 v14, v39, v39
	v_fmac_f32_e32 v14, v41, v41
	v_fmac_f32_e32 v14, v50, v50
	v_fmac_f32_e32 v14, v56, v56
	v_fmac_f32_e32 v14, v51, v51
	v_fmac_f32_e32 v14, v52, v52
	v_fmac_f32_e32 v14, v53, v53
	v_fmac_f32_e32 v14, v54, v54
	v_fmac_f32_e32 v14, v55, v55
	v_fmac_f32_e32 v14, v57, v57
	v_fmac_f32_e32 v14, v58, v58
	v_fmac_f32_e32 v14, v59, v59
	v_fmac_f32_e32 v14, v42, v42
	v_fmac_f32_e32 v14, v43, v43
	v_fmac_f32_e32 v14, v44, v44
	v_fmac_f32_e32 v14, v45, v45
	v_fmac_f32_e32 v14, v46, v46
	v_fmac_f32_e32 v14, v47, v47
	v_fmac_f32_e32 v14, v48, v48
	v_fmac_f32_e32 v14, v49, v49
	v_fmac_f32_e32 v14, v40, v40
	v_fmac_f32_e32 v14, v38, v38
	v_fmac_f32_e32 v14, v36, v36
	v_fmac_f32_e32 v14, v35, v35
	v_fmac_f32_e32 v14, v33, v33
	v_fmac_f32_e32 v14, v32, v32
	v_fmac_f32_e32 v14, v30, v30
	v_fmac_f32_e32 v14, v28, v28
	v_fmac_f32_e32 v14, v81, v81
	v_fmac_f32_e32 v14, v80, v80
	v_fmac_f32_e32 v14, v79, v79
	v_fmac_f32_e32 v14, v78, v78
	v_fmac_f32_e32 v14, v75, v75
	v_fmac_f32_e32 v14, v74, v74
	v_fmac_f32_e32 v14, v71, v71
	v_fmac_f32_e32 v14, v70, v70
	v_fmac_f32_e32 v14, v66, v66
	v_fmac_f32_e32 v14, v65, v65
	v_fmac_f32_e32 v14, v64, v64
	v_fmac_f32_e32 v14, v63, v63
	v_fmac_f32_e32 v14, v62, v62
	v_fmac_f32_e32 v14, v61, v61
	v_fmac_f32_e32 v14, v25, v25
	v_fma_f32 v77, -v148, v19, v18
	v_fmac_f32_e32 v14, v24, v24
	v_and_b32_e32 v10, 0xffff0000, v15
	v_and_b32_e32 v11, 0xffff0000, v11
	v_fmac_f32_e32 v14, v77, v77
	v_fma_f32 v72, -v148, v11, v10
	v_lshlrev_b32_e32 v10, 16, v16
	v_lshlrev_b32_e32 v11, 16, v12
	v_fmac_f32_e32 v14, v76, v76
	v_fma_f32 v68, -v148, v11, v10
	v_and_b32_e32 v10, 0xffff0000, v16
	v_and_b32_e32 v11, 0xffff0000, v12
	v_fmac_f32_e32 v14, v73, v73
	v_fma_f32 v67, -v148, v11, v10
	v_fmac_f32_e32 v14, v72, v72
	v_and_b32_e32 v10, 0xffff0000, v17
	v_lshlrev_b32_e32 v11, 16, v17
	v_and_b32_e32 v12, 0xffff0000, v13
	v_lshlrev_b32_e32 v13, 16, v13
	v_fmac_f32_e32 v14, v68, v68
	v_pk_fma_f32 v[22:23], v[148:149], v[12:13], v[10:11] neg_lo:[1,0,0] neg_hi:[1,0,0]
	v_fmac_f32_e32 v14, v67, v67
	v_pk_mul_f32 v[10:11], v[22:23], v[22:23]
	v_and_b32_e32 v12, 0xffff0000, v82
	v_add_f32_e32 v11, v11, v14
	v_add_f32_e32 v14, v10, v11
	v_and_b32_e32 v10, 0xffff0000, v6
	v_lshlrev_b32_e32 v11, 16, v6
	v_lshlrev_b32_e32 v13, 16, v82
	v_pk_fma_f32 v[20:21], v[148:149], v[12:13], v[10:11] neg_lo:[1,0,0] neg_hi:[1,0,0]
	s_nop 0
	v_pk_mul_f32 v[10:11], v[20:21], v[20:21]
	s_nop 0
	v_add_f32_e32 v6, v11, v14
	v_add_f32_e32 v12, v10, v6
	v_and_b32_e32 v6, 0xffff0000, v7
	v_lshlrev_b32_e32 v7, 16, v7
	v_and_b32_e32 v10, 0xffff0000, v83
	v_lshlrev_b32_e32 v11, 16, v83
	v_pk_fma_f32 v[18:19], v[148:149], v[10:11], v[6:7] neg_lo:[1,0,0] neg_hi:[1,0,0]
	v_and_b32_e32 v10, 0xffff0000, v84
	v_pk_mul_f32 v[6:7], v[18:19], v[18:19]
	v_lshlrev_b32_e32 v11, 16, v84
	v_add_f32_e32 v7, v7, v12
	v_add_f32_e32 v12, v6, v7
	v_and_b32_e32 v6, 0xffff0000, v8
	v_lshlrev_b32_e32 v7, 16, v8
	v_pk_fma_f32 v[16:17], v[148:149], v[10:11], v[6:7] neg_lo:[1,0,0] neg_hi:[1,0,0]
	v_and_b32_e32 v8, 0xffff0000, v85
	v_pk_mul_f32 v[6:7], v[16:17], v[16:17]
	s_nop 0
	v_add_f32_e32 v7, v7, v12
	v_add_f32_e32 v10, v6, v7
	v_and_b32_e32 v6, 0xffff0000, v9
	v_lshlrev_b32_e32 v7, 16, v9
	v_lshlrev_b32_e32 v9, 16, v85
	v_pk_fma_f32 v[14:15], v[148:149], v[8:9], v[6:7] neg_lo:[1,0,0] neg_hi:[1,0,0]
	s_nop 0
	v_pk_mul_f32 v[6:7], v[14:15], v[14:15]
	s_nop 0
	v_add_f32_e32 v7, v7, v10
	v_add_f32_e32 v6, v6, v7
	ds_swizzle_b32 v7, v6 offset:swizzle(SWAP,1)
	s_waitcnt lgkmcnt(0)
	v_add_f32_e32 v6, v6, v7
	v_fmamk_f32 v6, v6, 0x3c000000, v185
	v_cmp_gt_f32_e32 vcc, s95, v6
	v_mul_f32_e32 v7, 0x4b800000, v6
	s_nop 0
	v_cndmask_b32_e32 v6, v6, v7, vcc
	v_rsq_f32_e32 v6, v6
	s_nop 0
	v_mul_f32_e32 v7, 0x45800000, v6
	v_cndmask_b32_e32 v6, v6, v7, vcc
	v_mul_f32_e32 v69, v156, v6
	v_mov_b32_e32 v6, v92
	v_mov_b32_e32 v7, v93
	v_mov_b32_e32 v8, v94
	v_mov_b32_e32 v9, v95
	v_mov_b32_e32 v10, v88
	v_mov_b32_e32 v11, v89
	v_mov_b32_e32 v12, v90
	v_mov_b32_e32 v13, v91
	v_mul_f32_e32 v29, v29, v69
	v_mul_f32_e32 v21, v21, v69
	v_mul_f32_e32 v20, v20, v69
	s_waitcnt vmcnt(0)
;     DI void* gp(int i) const { return (void*)(__attribute__((address_space(1))) void*)ld(i); }
; DI unsigned cvtpk(float lo, float hi) { unsigned r; asm volatile("v_cvt_pk_bf16_f32 %0, %1, %2" : "=v"(r) : "v"(lo), "v"(hi)); return r; }
; template <int DQK, int MODE>
; DI void attn_body(const AttnArgs& a, char* lds) {
;     ...
; #pragma unroll
;             for (int c = 0; c < 8; ++c) { const f32x4 g0 = *(const f32x4*)(gg + c * 8), g1 = *(const f32x4*)(gg + c * 8 + 4);
;                 u32x4 w; w.x = cvtpk(v[c * 8] * rn * g0[0], v[c * 8 + 1] * rn * g0[1]); w.y = cvtpk(v[c * 8 + 2] * rn * g0[2], v[c * 8 + 3] * rn * g0[3]);
;                 w.z = cvtpk(v[c * 8 + 4] * rn * g1[0], v[c * 8 + 5] * rn * g1[1]); w.w = cvtpk(v[c * 8 + 6] * rn * g1[2], v[c * 8 + 7] * rn * g1[3]);
;                 *(u32x4*)(gp + c * 8) = w; }
;         }
	v_mul_f32_e32 v10, v10, v29
	v_mul_f32_e32 v29, v31, v69
	v_mul_f32_e32 v11, v11, v29
	v_cvt_pk_bf16_f32 v10, v10, v11
	v_mul_f32_e32 v11, v34, v69
	v_mul_f32_e32 v11, v12, v11
	v_mul_f32_e32 v12, v37, v69
	v_mul_f32_e32 v12, v13, v12
	v_cvt_pk_bf16_f32 v11, v11, v12
	v_mul_f32_e32 v12, v39, v69
	v_mul_f32_e32 v6, v6, v12
	v_mul_f32_e32 v12, v41, v69
	v_mul_f32_e32 v7, v7, v12
	v_cvt_pk_bf16_f32 v12, v6, v7
	v_mul_f32_e32 v6, v50, v69
	v_mul_f32_e32 v7, v56, v69
	v_mul_f32_e32 v6, v8, v6
	v_mul_f32_e32 v7, v9, v7
	v_cvt_pk_bf16_f32 v13, v6, v7
	global_store_dwordx4 v[26:27], v[10:13], off
	v_mov_b32_e32 v6, v100
	v_mov_b32_e32 v7, v101
	v_mov_b32_e32 v8, v102
	v_mov_b32_e32 v9, v103
	s_nop 0
	v_mov_b32_e32 v10, v96
	v_mov_b32_e32 v11, v97
	v_mov_b32_e32 v12, v98
	v_mov_b32_e32 v13, v99
	v_mul_f32_e32 v29, v51, v69
	s_waitcnt vmcnt(0)
	v_mul_f32_e32 v10, v10, v29
	v_mul_f32_e32 v29, v52, v69
	v_mul_f32_e32 v11, v11, v29
	v_cvt_pk_bf16_f32 v10, v10, v11
	v_mul_f32_e32 v11, v53, v69
	v_mul_f32_e32 v11, v12, v11
	v_mul_f32_e32 v12, v54, v69
	v_mul_f32_e32 v12, v13, v12
	v_cvt_pk_bf16_f32 v11, v11, v12
	v_mul_f32_e32 v12, v55, v69
	v_mul_f32_e32 v6, v6, v12
	v_mul_f32_e32 v12, v57, v69
	v_mul_f32_e32 v7, v7, v12
	v_cvt_pk_bf16_f32 v12, v6, v7
	v_mul_f32_e32 v6, v58, v69
	v_mul_f32_e32 v7, v59, v69
	v_mul_f32_e32 v6, v8, v6
	v_mul_f32_e32 v7, v9, v7
	v_cvt_pk_bf16_f32 v13, v6, v7
	global_store_dwordx4 v[26:27], v[10:13], off offset:16
	v_mov_b32_e32 v6, v108
	v_mov_b32_e32 v7, v109
	v_mov_b32_e32 v8, v110
	v_mov_b32_e32 v9, v111
	s_nop 0
	v_mov_b32_e32 v10, v104
	v_mov_b32_e32 v11, v105
	v_mov_b32_e32 v12, v106
	v_mov_b32_e32 v13, v107
	v_mul_f32_e32 v29, v42, v69
	s_waitcnt vmcnt(0)
	v_mul_f32_e32 v10, v10, v29
	v_mul_f32_e32 v29, v43, v69
	v_mul_f32_e32 v11, v11, v29
	v_cvt_pk_bf16_f32 v10, v10, v11
	v_mul_f32_e32 v11, v44, v69
	v_mul_f32_e32 v11, v12, v11
	v_mul_f32_e32 v12, v45, v69
	v_mul_f32_e32 v12, v13, v12
	v_cvt_pk_bf16_f32 v11, v11, v12
	v_mul_f32_e32 v12, v46, v69
	v_mul_f32_e32 v6, v6, v12
	v_mul_f32_e32 v12, v47, v69
	v_mul_f32_e32 v7, v7, v12
	v_cvt_pk_bf16_f32 v12, v6, v7
	v_mul_f32_e32 v6, v48, v69
	v_mul_f32_e32 v7, v49, v69
	v_mul_f32_e32 v6, v8, v6
	v_mul_f32_e32 v7, v9, v7
	v_cvt_pk_bf16_f32 v13, v6, v7
	global_store_dwordx4 v[26:27], v[10:13], off offset:32
	v_mov_b32_e32 v6, v116
	v_mov_b32_e32 v7, v117
	v_mov_b32_e32 v8, v118
	v_mov_b32_e32 v9, v119
	s_nop 0
	v_mov_b32_e32 v10, v112
	v_mov_b32_e32 v11, v113
	v_mov_b32_e32 v12, v114
	v_mov_b32_e32 v13, v115
	v_mul_f32_e32 v29, v40, v69
	s_waitcnt vmcnt(0)
	v_mul_f32_e32 v10, v10, v29
	v_mul_f32_e32 v29, v38, v69
	v_mul_f32_e32 v11, v11, v29
	v_cvt_pk_bf16_f32 v10, v10, v11
	v_mul_f32_e32 v11, v36, v69
	v_mul_f32_e32 v11, v12, v11
	v_mul_f32_e32 v12, v35, v69
	v_mul_f32_e32 v12, v13, v12
	v_cvt_pk_bf16_f32 v11, v11, v12
	v_mul_f32_e32 v12, v33, v69
	v_mul_f32_e32 v6, v6, v12
	v_mul_f32_e32 v12, v32, v69
	v_mul_f32_e32 v7, v7, v12
	v_cvt_pk_bf16_f32 v12, v6, v7
	v_mul_f32_e32 v6, v30, v69
	v_mul_f32_e32 v7, v28, v69
	v_mul_f32_e32 v6, v8, v6
	v_mul_f32_e32 v7, v9, v7
	v_cvt_pk_bf16_f32 v13, v6, v7
	global_store_dwordx4 v[26:27], v[10:13], off offset:48
	v_mov_b32_e32 v6, v124
	v_mov_b32_e32 v7, v125
	v_mov_b32_e32 v8, v126
	v_mov_b32_e32 v9, v127
	s_nop 0
	v_mov_b32_e32 v10, v120
	v_mov_b32_e32 v11, v121
	v_mov_b32_e32 v12, v122
	v_mov_b32_e32 v13, v123
	v_mul_f32_e32 v28, v81, v69
	s_waitcnt vmcnt(0)
	v_mul_f32_e32 v10, v10, v28
	v_mul_f32_e32 v28, v80, v69
	v_mul_f32_e32 v11, v11, v28
	v_cvt_pk_bf16_f32 v10, v10, v11
	v_mul_f32_e32 v11, v79, v69
	v_mul_f32_e32 v11, v12, v11
	v_mul_f32_e32 v12, v78, v69
	v_mul_f32_e32 v12, v13, v12
	v_cvt_pk_bf16_f32 v11, v11, v12
	v_mul_f32_e32 v12, v75, v69
	v_mul_f32_e32 v6, v6, v12
	v_mul_f32_e32 v12, v74, v69
	v_mul_f32_e32 v7, v7, v12
	v_cvt_pk_bf16_f32 v12, v6, v7
	v_mul_f32_e32 v6, v71, v69
	v_mul_f32_e32 v7, v70, v69
	v_mul_f32_e32 v6, v8, v6
	v_mul_f32_e32 v7, v9, v7
	v_cvt_pk_bf16_f32 v13, v6, v7
	global_store_dwordx4 v[26:27], v[10:13], off offset:64
	v_mov_b32_e32 v6, v200
	v_mov_b32_e32 v7, v201
	v_mov_b32_e32 v8, v202
	v_mov_b32_e32 v9, v203
	s_nop 0
	v_mov_b32_e32 v10, v196
	v_mov_b32_e32 v11, v197
	v_mov_b32_e32 v12, v198
	v_mov_b32_e32 v13, v199
	v_mul_f32_e32 v28, v66, v69
	s_waitcnt vmcnt(0)
	v_mul_f32_e32 v10, v10, v28
	v_mul_f32_e32 v28, v65, v69
	v_mul_f32_e32 v11, v11, v28
	v_cvt_pk_bf16_f32 v10, v10, v11
	v_mul_f32_e32 v11, v64, v69
	v_mul_f32_e32 v11, v12, v11
	v_mul_f32_e32 v12, v63, v69
	v_mul_f32_e32 v12, v13, v12
	v_cvt_pk_bf16_f32 v11, v11, v12
	v_mul_f32_e32 v12, v62, v69
	v_mul_f32_e32 v6, v6, v12
	v_mul_f32_e32 v12, v61, v69
	v_mul_f32_e32 v7, v7, v12
	v_cvt_pk_bf16_f32 v12, v6, v7
	v_mul_f32_e32 v6, v25, v69
	v_mul_f32_e32 v7, v24, v69
	v_mul_f32_e32 v6, v8, v6
	v_mul_f32_e32 v7, v9, v7
	v_cvt_pk_bf16_f32 v13, v6, v7
	global_store_dwordx4 v[26:27], v[10:13], off offset:80
	v_mov_b32_e32 v6, v208
	v_mov_b32_e32 v7, v209
	v_mov_b32_e32 v8, v210
	v_mov_b32_e32 v9, v211
	s_nop 0
	v_mov_b32_e32 v10, v204
	v_mov_b32_e32 v11, v205
	v_mov_b32_e32 v12, v206
	v_mov_b32_e32 v13, v207
	v_mul_f32_e32 v24, v77, v69
	s_waitcnt vmcnt(0)
	v_mul_f32_e32 v10, v10, v24
	v_mul_f32_e32 v24, v76, v69
	v_mul_f32_e32 v11, v11, v24
	v_cvt_pk_bf16_f32 v10, v10, v11
	v_mul_f32_e32 v11, v73, v69
	v_mul_f32_e32 v11, v12, v11
	v_mul_f32_e32 v12, v72, v69
	v_mul_f32_e32 v12, v13, v12
	v_cvt_pk_bf16_f32 v11, v11, v12
	v_mul_f32_e32 v12, v68, v69
	v_mul_f32_e32 v6, v6, v12
	v_mul_f32_e32 v12, v67, v69
	v_mul_f32_e32 v7, v7, v12
	v_cvt_pk_bf16_f32 v12, v6, v7
	v_mul_f32_e32 v6, v23, v69
	v_mul_f32_e32 v7, v22, v69
	v_mul_f32_e32 v6, v8, v6
	v_mul_f32_e32 v7, v9, v7
	v_cvt_pk_bf16_f32 v13, v6, v7
	global_store_dwordx4 v[26:27], v[10:13], off offset:96
	v_mov_b32_e32 v6, v216
	v_mov_b32_e32 v7, v217
	v_mov_b32_e32 v8, v218
	v_mov_b32_e32 v9, v219
	s_nop 0
	v_mov_b32_e32 v10, v212
	v_mov_b32_e32 v11, v213
	v_mov_b32_e32 v12, v214
	v_mov_b32_e32 v13, v215
	s_waitcnt vmcnt(0)
	v_mul_f32_e32 v10, v10, v21
	v_mul_f32_e32 v11, v11, v20
	v_cvt_pk_bf16_f32 v10, v10, v11
	v_mul_f32_e32 v11, v19, v69
	v_mul_f32_e32 v11, v12, v11
	v_mul_f32_e32 v12, v18, v69
	v_mul_f32_e32 v12, v13, v12
	v_cvt_pk_bf16_f32 v11, v11, v12
	v_mul_f32_e32 v12, v17, v69
	v_mul_f32_e32 v6, v6, v12
	v_mul_f32_e32 v12, v16, v69
	v_mul_f32_e32 v7, v7, v12
	v_cvt_pk_bf16_f32 v12, v6, v7
	v_mul_f32_e32 v6, v15, v69
	v_mul_f32_e32 v7, v14, v69
	v_mul_f32_e32 v6, v8, v6
	v_mul_f32_e32 v7, v9, v7
	v_cvt_pk_bf16_f32 v13, v6, v7
	global_store_dwordx4 v[26:27], v[10:13], off offset:112
	s_cbranch_execnz .LBB0_736

; DI float bf2f(unsigned short b) { return __uint_as_float(((unsigned)b) << 16); }
; DI unsigned short f2bf(float f) { return (unsigned short)(cvtpk(f, f) & 0xffffu); }
; template <int DQK, int MODE>
; DI void attn_body(const AttnArgs& a, char* lds) {
;     ...
;     const bf16_t* Qw = a.Q + (size_t)(wid * 32 + r32) * a.ldq + hi * 8;
; #pragma unroll
;     for (int d0 = 0; d0 < NQR; ++d0) qr[d0] = *(const bf16x8*)(Qw + d0 * 16);
;     if constexpr (MODE == 2) {
;         const f32x2* rp = a.rope + (size_t)(a.qpos0 + wid * 32 + r32) * 32 + hi * 8;
; #pragma unroll
;         for (int dd = 0; dd < 2; ++dd) {
;             bf16x8 x1 = *(const bf16x8*)(Qw + (8 + dd) * 16), x2 = *(const bf16x8*)(Qw + (10 + dd) * 16); bf16x8 y1, y2;
; #pragma unroll
;             for (int j = 0; j < 8; ++j) { const f32x2 cs = rp[dd * 16 + j]; const float a1 = bf2f((unsigned short)x1[j]), a2 = bf2f((unsigned short)x2[j]);
;                 y1[j] = (short)f2bf(a1 * cs.x - a2 * cs.y); y2[j] = (short)f2bf(a1 * cs.y + a2 * cs.x); }
; template <int TYPE>
; DI void attn_phase(const Params& P, int l, unsigned char* shm, const int rep, const bool cross = false) {
;     ...
;         const int idx = *sidx;
;         if (idx >= (cross ? 256 : 512)) break;
;         const bool sample = idx < 256; const int w = idx & 255, head = w >> 5, qbl = w & 31;
;         const int t0 = (sample ? 32 + qbl : qbl) * 256;
;         const int seqstart = sample ? 8192 : (qbl < 16 ? 0 : 4096), seqlen = sample ? 8192 : 4096;
.LBB0_767:
	s_or_b64 exec, exec, s[4:5]
	v_mov_b32_e32 v0, s88
	s_waitcnt lgkmcnt(0)
	s_barrier
	ds_read_b32 v0, v0
	s_mov_b64 s[4:5], -1
	s_waitcnt lgkmcnt(0)
	v_cmp_lt_i32_e32 vcc, s48, v0
	v_readfirstlane_b32 s10, v0
	s_cbranch_vccnz .LBB0_762
	s_lshl_b32 s4, s10, 8
	s_and_b32 s16, s4, 0x1f00
	s_bfe_u32 s28, s10, 0x30005
	s_or_b32 s17, s16, 0x2000
	s_and_b32 s20, s4, 0x1000
	s_cmpk_lt_i32 s10, 0x100
	s_cselect_b64 s[4:5], -1, 0
	s_and_b64 s[10:11], s[4:5], exec
	s_cselect_b32 s29, s17, s16
	s_cselect_b32 s20, 0x2000, s20
	s_sub_i32 s33, s29, s20
	s_mul_i32 s10, s29, 0xc00
	s_add_u32 s10, s24, s10
	s_addc_u32 s11, s25, 0
	s_mul_i32 s16, s28, 0x180
	v_mov_b32_e32 v133, v132
	s_add_u32 s16, s10, s16
	s_addc_u32 s17, s11, 0
	v_ashrrev_i32_e32 v15, 6, v133
	v_and_b32_e32 v136, 31, v133
	v_lshlrev_b32_e32 v135, 5, v15
	v_bfe_u32 v137, v133, 5, 1
	v_or_b32_e32 v0, v135, v136
	v_mov_b64_e32 v[2:3], s[16:17]
	s_movk_i32 s16, 0xc00
	v_mad_i64_i32 v[2:3], s[16:17], v0, s16, v[2:3]
	v_lshlrev_b32_e32 v114, 4, v137
	v_mov_b32_e32 v115, v1
	v_lshl_add_u64 v[10:11], v[2:3], 0, v[114:115]
	v_add_u32_e32 v2, s33, v0
	v_ashrrev_i32_e32 v3, 31, v2
	v_lshlrev_b64 v[2:3], 8, v[2:3]
	v_lshl_add_u64 v[2:3], s[8:9], 0, v[2:3]
	v_lshlrev_b32_e32 v0, 6, v137
	s_barrier
	global_load_dwordx4 v[98:101], v[10:11], off
	global_load_dwordx4 v[102:105], v[10:11], off offset:32
	global_load_dwordx4 v[106:109], v[10:11], off offset:64
	global_load_dwordx4 v[110:113], v[10:11], off offset:96
	v_lshl_add_u64 v[12:13], v[2:3], 0, v[0:1]
	global_load_dwordx2 v[172:173], v[12:13], off offset:8
	global_load_dwordx2 v[174:175], v[12:13], off offset:16
	global_load_dwordx2 v[176:177], v[12:13], off offset:24
	global_load_dwordx2 v[178:179], v[12:13], off offset:32
	global_load_dwordx2 v[194:195], v[12:13], off offset:40
	global_load_dwordx2 v[196:197], v[12:13], off offset:48
	global_load_dwordx2 v[198:199], v[12:13], off offset:56
	global_load_dwordx2 v[200:201], v[12:13], off offset:136
	global_load_dwordx2 v[202:203], v[12:13], off offset:144
	global_load_dwordx2 v[204:205], v[12:13], off offset:152
	global_load_dwordx2 v[206:207], v[12:13], off offset:160
	global_load_dwordx2 v[208:209], v[12:13], off offset:168
	global_load_dwordx2 v[210:211], v[12:13], off offset:176
	global_load_dwordx2 v[212:213], v[12:13], off offset:184
	global_load_dwordx4 v[2:5], v[10:11], off offset:256
	global_load_dwordx4 v[6:9], v[10:11], off offset:320
	global_load_dwordx2 v[16:17], v[12:13], off
	v_and_b32_e32 v134, 63, v133
	v_lshlrev_b32_e32 v138, 13, v15
	v_lshlrev_b32_e32 v14, 4, v134
	s_mov_b32 s16, 0x5040100
	v_add3_u32 v139, s49, v138, v14
	s_lshl_b32 s10, s20, 12
	s_add_u32 s10, s15, s10
	s_addc_u32 s11, s22, 0
	s_lshl_b32 s35, s28, 9
	s_add_u32 s10, s10, s35
	s_addc_u32 s11, s11, 0
	s_mulk_i32 s20, 0x5c00
	s_add_u32 s20, s14, s20
	s_addc_u32 s35, s12, 0
	s_add_u32 s50, s20, 0x4c82a00
	s_addc_u32 s51, s35, 0
	s_waitcnt vmcnt(2)
	v_lshlrev_b32_e32 v19, 16, v2
	s_waitcnt vmcnt(1)
	v_lshlrev_b32_e32 v18, 16, v6
	s_waitcnt vmcnt(0)
	v_pk_mul_f32 v[20:21], v[16:17], v[18:19] op_sel:[0,1] op_sel_hi:[1,0]
	v_pk_mul_f32 v[16:17], v[16:17], v[18:19]
	v_sub_f32_e32 v0, v20, v21
	v_add_f32_e32 v16, v17, v16
	v_cvt_pk_bf16_f32 v0, v0, v0
	v_cvt_pk_bf16_f32 v22, v16, v16
	v_mov_b32_e32 v16, v172
	v_mov_b32_e32 v17, v173
	v_and_b32_e32 v19, 0xffff0000, v2
	v_and_b32_e32 v18, 0xffff0000, v6
	s_waitcnt vmcnt(0)
	v_pk_mul_f32 v[20:21], v[16:17], v[18:19] op_sel:[0,1] op_sel_hi:[1,0]
	s_nop 0
	v_sub_f32_e32 v2, v20, v21
	v_pk_mul_f32 v[16:17], v[16:17], v[18:19]
	v_cvt_pk_bf16_f32 v23, v2, v2
	v_lshlrev_b32_e32 v19, 16, v3
	v_add_f32_e32 v2, v17, v16
	v_cvt_pk_bf16_f32 v24, v2, v2
	v_mov_b32_e32 v16, v174
	v_mov_b32_e32 v17, v175
	v_lshlrev_b32_e32 v18, 16, v7
	v_and_b32_e32 v3, 0xffff0000, v3
	s_waitcnt vmcnt(0)
	v_pk_mul_f32 v[20:21], v[16:17], v[18:19] op_sel:[0,1] op_sel_hi:[1,0]
	s_nop 0
	v_sub_f32_e32 v2, v20, v21
	v_pk_mul_f32 v[16:17], v[16:17], v[18:19]
	v_cvt_pk_bf16_f32 v20, v2, v2
	s_nop 0
	v_add_f32_e32 v2, v17, v16
	v_cvt_pk_bf16_f32 v18, v2, v2
	v_mov_b32_e32 v16, v176
	v_mov_b32_e32 v17, v177
	v_and_b32_e32 v2, 0xffff0000, v7
	s_waitcnt vmcnt(0)
	v_pk_mul_f32 v[6:7], v[16:17], v[2:3] op_sel:[0,1] op_sel_hi:[1,0]
	v_pk_mul_f32 v[2:3], v[16:17], v[2:3]
	v_sub_f32_e32 v6, v6, v7
	v_add_f32_e32 v2, v3, v2
	v_cvt_pk_bf16_f32 v19, v6, v6
	v_cvt_pk_bf16_f32 v21, v2, v2
	v_mov_b32_e32 v2, v178
	v_mov_b32_e32 v3, v179
	v_lshlrev_b32_e32 v7, 16, v4
	v_lshlrev_b32_e32 v6, 16, v8
	s_waitcnt vmcnt(0)
	v_pk_mul_f32 v[16:17], v[2:3], v[6:7] op_sel:[0,1] op_sel_hi:[1,0]
	v_pk_mul_f32 v[2:3], v[2:3], v[6:7]
	v_sub_f32_e32 v16, v16, v17
	v_add_f32_e32 v2, v3, v2
	v_cvt_pk_bf16_f32 v25, v16, v16
	v_cvt_pk_bf16_f32 v26, v2, v2
	v_mov_b32_e32 v2, v194
	v_mov_b32_e32 v3, v195
	v_and_b32_e32 v7, 0xffff0000, v4
	v_and_b32_e32 v6, 0xffff0000, v8
	s_waitcnt vmcnt(0)
	v_pk_mul_f32 v[16:17], v[2:3], v[6:7] op_sel:[0,1] op_sel_hi:[1,0]
	v_pk_mul_f32 v[2:3], v[2:3], v[6:7]
	v_sub_f32_e32 v4, v16, v17
	v_add_f32_e32 v2, v3, v2
	v_cvt_pk_bf16_f32 v4, v4, v4
	v_cvt_pk_bf16_f32 v8, v2, v2
	v_mov_b32_e32 v2, v196
	v_mov_b32_e32 v3, v197
	v_lshlrev_b32_e32 v7, 16, v5
	v_lshlrev_b32_e32 v6, 16, v9
	v_perm_b32 v4, v4, v25, s16
	v_perm_b32 v8, v8, v26, s16
	s_waitcnt vmcnt(0)
	v_pk_mul_f32 v[16:17], v[2:3], v[6:7] op_sel:[0,1] op_sel_hi:[1,0]
	v_pk_mul_f32 v[2:3], v[2:3], v[6:7]
	v_sub_f32_e32 v16, v16, v17
	v_cvt_pk_bf16_f32 v27, v16, v16
	v_add_f32_e32 v2, v3, v2
	v_cvt_pk_bf16_f32 v28, v2, v2
	v_mov_b32_e32 v6, v198
	v_mov_b32_e32 v7, v199
	v_and_b32_e32 v17, 0xffff0000, v5
	v_and_b32_e32 v16, 0xffff0000, v9
	s_waitcnt vmcnt(0)
; DI float bf2f(unsigned short b) { return __uint_as_float(((unsigned)b) << 16); }
; DI unsigned short f2bf(float f) { return (unsigned short)(cvtpk(f, f) & 0xffffu); }
; template <int DQK, int MODE>
; DI void attn_body(const AttnArgs& a, char* lds) {
;     ...
; #pragma unroll
;         for (int dd = 0; dd < 2; ++dd) {
;             bf16x8 x1 = *(const bf16x8*)(Qw + (8 + dd) * 16), x2 = *(const bf16x8*)(Qw + (10 + dd) * 16); bf16x8 y1, y2;
; #pragma unroll
;             for (int j = 0; j < 8; ++j) { const f32x2 cs = rp[dd * 16 + j]; const float a1 = bf2f((unsigned short)x1[j]), a2 = bf2f((unsigned short)x2[j]);
;                 y1[j] = (short)f2bf(a1 * cs.x - a2 * cs.y); y2[j] = (short)f2bf(a1 * cs.y + a2 * cs.x); }
;             *(bf16x8*)(qrl + (8 + dd - NQR) * 1024) = y1; *(bf16x8*)(qrl + (10 + dd - NQR) * 1024) = y2; }
; #pragma unroll
;         for (int d0 = NQR; d0 < 8; ++d0) *(bf16x8*)(qrl + (d0 - NQR) * 1024) = *(const bf16x8*)(Qw + d0 * 16);
	v_pk_mul_f32 v[2:3], v[6:7], v[16:17] op_sel:[0,1] op_sel_hi:[1,0]
	s_nop 0
	v_sub_f32_e32 v2, v2, v3
	v_cvt_pk_bf16_f32 v5, v2, v2
	v_pk_mul_f32 v[6:7], v[6:7], v[16:17]
	v_perm_b32 v2, v23, v0, s16
	v_perm_b32 v3, v19, v20, s16
	v_perm_b32 v5, v5, v27, s16
	v_add_f32_e32 v0, v7, v6
	v_cvt_pk_bf16_f32 v0, v0, v0
	v_perm_b32 v6, v24, v22, s16
	v_perm_b32 v7, v21, v18, s16
	v_perm_b32 v9, v0, v28, s16
	ds_write_b128 v139, v[2:5] offset:4096
	ds_write_b128 v139, v[6:9] offset:6144
	global_load_dwordx4 v[2:5], v[10:11], off offset:288
	global_load_dwordx4 v[6:9], v[10:11], off offset:352
	global_load_dwordx2 v[16:17], v[12:13], off offset:128
	s_waitcnt vmcnt(2)
	v_lshlrev_b32_e32 v19, 16, v2
	s_waitcnt vmcnt(1)
	v_lshlrev_b32_e32 v18, 16, v6
	s_waitcnt vmcnt(0)
	v_pk_mul_f32 v[20:21], v[16:17], v[18:19] op_sel:[0,1] op_sel_hi:[1,0]
	v_pk_mul_f32 v[16:17], v[16:17], v[18:19]
	v_sub_f32_e32 v0, v20, v21
	v_add_f32_e32 v16, v17, v16
	v_cvt_pk_bf16_f32 v0, v0, v0
	v_cvt_pk_bf16_f32 v22, v16, v16
	v_mov_b32_e32 v16, v200
	v_mov_b32_e32 v17, v201
	v_and_b32_e32 v19, 0xffff0000, v2
	v_and_b32_e32 v18, 0xffff0000, v6
	s_waitcnt vmcnt(0)
	v_pk_mul_f32 v[20:21], v[16:17], v[18:19] op_sel:[0,1] op_sel_hi:[1,0]
	s_nop 0
	v_sub_f32_e32 v2, v20, v21
	v_pk_mul_f32 v[16:17], v[16:17], v[18:19]
	v_cvt_pk_bf16_f32 v23, v2, v2
	v_lshlrev_b32_e32 v19, 16, v3
	v_add_f32_e32 v2, v17, v16
	v_cvt_pk_bf16_f32 v24, v2, v2
	v_mov_b32_e32 v16, v202
	v_mov_b32_e32 v17, v203
	v_lshlrev_b32_e32 v18, 16, v7
	v_and_b32_e32 v3, 0xffff0000, v3
	s_waitcnt vmcnt(0)
	v_pk_mul_f32 v[20:21], v[16:17], v[18:19] op_sel:[0,1] op_sel_hi:[1,0]
	s_nop 0
	v_sub_f32_e32 v2, v20, v21
	v_pk_mul_f32 v[16:17], v[16:17], v[18:19]
	v_cvt_pk_bf16_f32 v20, v2, v2
	s_nop 0
	v_add_f32_e32 v2, v17, v16
	v_cvt_pk_bf16_f32 v18, v2, v2
	v_mov_b32_e32 v16, v204
	v_mov_b32_e32 v17, v205
	v_and_b32_e32 v2, 0xffff0000, v7
	s_waitcnt vmcnt(0)
	v_pk_mul_f32 v[6:7], v[16:17], v[2:3] op_sel:[0,1] op_sel_hi:[1,0]
	v_pk_mul_f32 v[2:3], v[16:17], v[2:3]
	v_sub_f32_e32 v6, v6, v7
	v_add_f32_e32 v2, v3, v2
	v_cvt_pk_bf16_f32 v19, v6, v6
	v_cvt_pk_bf16_f32 v21, v2, v2
	v_mov_b32_e32 v2, v206
	v_mov_b32_e32 v3, v207
	v_lshlrev_b32_e32 v7, 16, v4
	v_lshlrev_b32_e32 v6, 16, v8
	s_waitcnt vmcnt(0)
	v_pk_mul_f32 v[16:17], v[2:3], v[6:7] op_sel:[0,1] op_sel_hi:[1,0]
	v_pk_mul_f32 v[2:3], v[2:3], v[6:7]
	v_sub_f32_e32 v16, v16, v17
	v_add_f32_e32 v2, v3, v2
	v_cvt_pk_bf16_f32 v25, v16, v16
	v_cvt_pk_bf16_f32 v26, v2, v2
	v_mov_b32_e32 v2, v208
	v_mov_b32_e32 v3, v209
	v_and_b32_e32 v7, 0xffff0000, v4
	v_and_b32_e32 v6, 0xffff0000, v8
	s_waitcnt vmcnt(0)
	v_pk_mul_f32 v[16:17], v[2:3], v[6:7] op_sel:[0,1] op_sel_hi:[1,0]
	v_pk_mul_f32 v[2:3], v[2:3], v[6:7]
	v_sub_f32_e32 v4, v16, v17
	v_add_f32_e32 v2, v3, v2
	v_cvt_pk_bf16_f32 v4, v4, v4
	v_cvt_pk_bf16_f32 v8, v2, v2
	v_mov_b32_e32 v2, v210
	v_mov_b32_e32 v3, v211
	v_lshlrev_b32_e32 v7, 16, v5
	v_lshlrev_b32_e32 v6, 16, v9
	v_perm_b32 v4, v4, v25, s16
	v_perm_b32 v8, v8, v26, s16
	s_waitcnt vmcnt(0)
	v_pk_mul_f32 v[16:17], v[2:3], v[6:7] op_sel:[0,1] op_sel_hi:[1,0]
	s_nop 0
	v_sub_f32_e32 v16, v16, v17
	v_pk_mul_f32 v[2:3], v[2:3], v[6:7]
	v_cvt_pk_bf16_f32 v16, v16, v16
	s_nop 0
	v_add_f32_e32 v2, v3, v2
	v_cvt_pk_bf16_f32 v17, v2, v2
	v_mov_b32_e32 v6, v212
	v_mov_b32_e32 v7, v213
	v_and_b32_e32 v13, 0xffff0000, v5
	v_and_b32_e32 v12, 0xffff0000, v9
	s_waitcnt vmcnt(0)
	v_pk_mul_f32 v[2:3], v[6:7], v[12:13] op_sel:[0,1] op_sel_hi:[1,0]
	s_nop 0
	v_sub_f32_e32 v2, v2, v3
	v_cvt_pk_bf16_f32 v5, v2, v2
	v_pk_mul_f32 v[6:7], v[6:7], v[12:13]
	v_perm_b32 v2, v23, v0, s16
	v_perm_b32 v3, v19, v20, s16
	v_perm_b32 v5, v5, v16, s16
	v_add_f32_e32 v0, v7, v6
	v_cvt_pk_bf16_f32 v0, v0, v0
	v_perm_b32 v6, v24, v22, s16
	v_perm_b32 v7, v21, v18, s16
	v_perm_b32 v9, v0, v17, s16
	ds_write_b128 v139, v[2:5] offset:5120
	ds_write_b128 v139, v[6:9] offset:7168
	global_load_dwordx4 v[2:5], v[10:11], off offset:128
	s_waitcnt vmcnt(0)
	ds_write_b128 v139, v[2:5]
	global_load_dwordx4 v[2:5], v[10:11], off offset:160
	s_waitcnt vmcnt(0)
	ds_write_b128 v139, v[2:5] offset:1024
	global_load_dwordx4 v[2:5], v[10:11], off offset:192
	s_waitcnt vmcnt(0)
	ds_write_b128 v139, v[2:5] offset:2048
	global_load_dwordx4 v[2:5], v[10:11], off offset:224
	s_waitcnt vmcnt(0)
; #define DMA(buf, k0) do { _Pragma("unroll") for (int _i = 0; _i < NI; ++_i) { \
;         char* _d = (_i < 2) ? V_lds + (buf) * SHM_V + (wu + 8 * _i) * 1024 : K_lds + (buf) * SHM_K + (wu + 8 * _i - 16) * 1024; \
;         __builtin_amdgcn_global_load_lds((const unsigned*)(sp[_i] + (size_t)(k0) * sld[_i]), (LAS unsigned*)_d, 16, 0, 0); } } while (0)
; template <int DQK, int MODE>
; DI void attn_body(const AttnArgs& a, char* lds) {
;     ...
;     constexpr int NI = 2 + KCH;
;     const bf16_t* sp[NI]; int sld[NI];
; #pragma unroll
;     for (int i = 0; i < NI; ++i) { const int b = wid + 8 * i;
;         if (i < 2) { const int pos = b * 1024 + lane * 16, stl = pos >> 9, q = (pos & 511) >> 1, kk = (stl >> 2) * 8 + (q >> 5), c = (stl & 3) * 32 + (q & 31);
;             const int k = (kk & ~0xC) | ((kk & 4) << 1) | ((kk & 8) >> 1);
;             sp[i] = a.V + (size_t)k * a.ldv + c; sld[i] = a.ldv;
;         } else { const int pos = (b - 16) * 1024 + lane * 16, row = pos / KROWB, within = pos - row * KROWB, c = (within ^ ksw(row)) >> 4;
;             if (MODE == 2 && c >= 16) { sp[i] = a.K2 + (size_t)row * a.ldk2 + (c - 16) * 8; sld[i] = a.ldk2; }
;             else { sp[i] = a.K + (size_t)row * a.ldk + c * 8; sld[i] = a.ldk; } } }
;     const int wu = __builtin_amdgcn_readfirstlane(wid);
;     ...
;     DMA(0, 0); asm volatile("s_waitcnt vmcnt(0)" ::: "memory"); __syncthreads();
;     if (wid >= 4) __builtin_amdgcn_s_setprio(1);
	ds_write_b128 v139, v[2:5] offset:3072
	v_lshl_or_b32 v4, v15, 10, v14
	v_mul_hi_i32 v0, v4, s47
	v_lshrrev_b32_e32 v2, 31, v0
	v_ashrrev_i32_e32 v0, 6, v0
	v_add_u32_e32 v2, v0, v2
	v_mad_i32_i24 v0, v2, s53, v4
	v_lshlrev_b32_e32 v3, 3, v2
	v_bitop3_b32 v0, v0, v3, s34 bitop3:0x78
	v_cmp_gt_i32_e32 vcc, s56, v0
	v_ashrrev_i32_e32 v3, 31, v2
	s_and_saveexec_b64 s[16:17], vcc
	s_xor_b64 s[54:55], exec, s[16:17]
	v_lshlrev_b64 v[2:3], 12, v[2:3]
	v_ashrrev_i32_e32 v6, 1, v0
	v_lshl_add_u64 v[2:3], s[10:11], 0, v[2:3]
	v_ashrrev_i32_e32 v7, 31, v6
	v_lshl_add_u64 v[116:117], v[6:7], 1, v[2:3]
	s_or_saveexec_b64 s[54:55], s[54:55]
	v_mov_b64_e32 v[118:119], 0x800
	s_xor_b64 exec, exec, s[54:55]
	v_mul_hi_i32_i24_e32 v3, 0x5c00, v2
	v_mul_i32_i24_e32 v2, 0x5c00, v2
	v_lshl_add_u64 v[2:3], s[50:51], 0, v[2:3]
	v_lshl_add_u64 v[2:3], v[2:3], 0, v[0:1]
	v_lshl_add_u64 v[116:117], v[2:3], 0, s[60:61]
	v_mov_b64_e32 v[118:119], 0x2e00
	s_or_b64 exec, exec, s[54:55]
	v_add_u32_e32 v4, 0xffffc000, v4
	v_add_u32_e32 v0, 0x6000, v4
	v_mul_hi_i32 v2, v0, s47
	v_lshrrev_b32_e32 v3, 31, v2
	v_ashrrev_i32_e32 v2, 6, v2
	v_add_u32_e32 v2, v2, v3
	v_mad_i32_i24 v0, v2, s53, v0
	v_lshlrev_b32_e32 v3, 3, v2
	v_bitop3_b32 v0, v0, v3, s34 bitop3:0x78
	v_cmp_gt_i32_e32 vcc, s56, v0
	v_ashrrev_i32_e32 v3, 31, v2
	s_and_saveexec_b64 s[16:17], vcc
	s_xor_b64 s[54:55], exec, s[16:17]
	v_lshlrev_b64 v[2:3], 12, v[2:3]
	v_ashrrev_i32_e32 v6, 1, v0
	v_lshl_add_u64 v[2:3], s[10:11], 0, v[2:3]
	v_ashrrev_i32_e32 v7, 31, v6
	v_lshl_add_u64 v[120:121], v[6:7], 1, v[2:3]
	s_or_saveexec_b64 s[54:55], s[54:55]
	v_mov_b64_e32 v[122:123], 0x800
	s_xor_b64 exec, exec, s[54:55]
	v_mul_hi_i32_i24_e32 v3, 0x5c00, v2
	v_mul_i32_i24_e32 v2, 0x5c00, v2
	v_lshl_add_u64 v[2:3], s[50:51], 0, v[2:3]
	v_lshl_add_u64 v[2:3], v[2:3], 0, v[0:1]
	v_lshl_add_u64 v[120:121], v[2:3], 0, s[60:61]
	v_mov_b64_e32 v[122:123], 0x2e00
	s_or_b64 exec, exec, s[54:55]
	v_add_u32_e32 v0, 0x8000, v4
	v_mul_hi_i32 v2, v0, s47
	v_lshrrev_b32_e32 v3, 31, v2
	v_ashrrev_i32_e32 v2, 6, v2
	v_add_u32_e32 v2, v2, v3
	v_mad_i32_i24 v0, v2, s53, v0
	v_lshlrev_b32_e32 v3, 3, v2
	v_bitop3_b32 v0, v0, v3, s34 bitop3:0x78
	v_cmp_gt_i32_e32 vcc, s56, v0
	v_ashrrev_i32_e32 v3, 31, v2
	s_and_saveexec_b64 s[16:17], vcc
	s_xor_b64 s[54:55], exec, s[16:17]
	v_lshlrev_b64 v[2:3], 12, v[2:3]
	v_ashrrev_i32_e32 v4, 1, v0
	v_lshl_add_u64 v[2:3], s[10:11], 0, v[2:3]
	v_ashrrev_i32_e32 v5, 31, v4
	v_lshl_add_u64 v[124:125], v[4:5], 1, v[2:3]
	s_or_saveexec_b64 s[54:55], s[54:55]
	v_mov_b64_e32 v[126:127], 0x800
	s_xor_b64 exec, exec, s[54:55]
	v_mul_hi_i32_i24_e32 v3, 0x5c00, v2
	v_mul_i32_i24_e32 v2, 0x5c00, v2
	v_lshl_add_u64 v[2:3], s[50:51], 0, v[2:3]
	v_lshl_add_u64 v[2:3], v[2:3], 0, v[0:1]
	v_lshl_add_u64 v[124:125], v[2:3], 0, s[60:61]
	v_mov_b64_e32 v[126:127], 0x2e00
	s_or_b64 exec, exec, s[54:55]
	v_lshlrev_b32_e32 v3, 3, v134
	v_and_b32_e32 v2, 24, v3
	v_bfe_u32 v0, v133, 2, 2
	v_and_or_b32 v4, v133, s13, v2
	v_lshrrev_b32_e32 v5, 1, v133
	v_bfe_u32 v8, v133, 2, 3
	v_lshlrev_b32_e32 v0, 1, v4
	v_lshl_add_u64 v[4:5], s[10:11], 0, v[0:1]
	v_lshlrev_b32_e32 v0, 2, v15
	v_lshlrev_b32_e32 v6, 2, v15
	v_and_b32_e32 v0, -16, v0
	v_and_b32_e32 v9, 8, v6
	v_or3_b32 v6, v8, v9, v0
	v_or3_b32 v0, v0, v9, v8
	v_ashrrev_i32_e32 v7, 31, v6
	v_add_u32_e32 v8, 32, v0
	v_readfirstlane_b32 s10, v15
	v_lshlrev_b64 v[6:7], 12, v[6:7]
	v_ashrrev_i32_e32 v9, 31, v8
	s_lshl_b32 s10, s10, 10
	v_lshl_add_u64 v[128:129], v[4:5], 0, v[6:7]
	v_lshlrev_b64 v[8:9], 12, v[8:9]
	s_add_i32 s16, s10, 0
	v_lshl_add_u64 v[6:7], v[128:129], 0, s[58:59]
	v_lshl_add_u64 v[130:131], v[4:5], 0, v[8:9]
	s_mov_b32 m0, s16
	v_lshl_add_u64 v[4:5], v[130:131], 0, s[58:59]
	s_add_i32 s10, s16, 0x8000
	global_load_lds_dwordx4 v[6:7], off
	s_add_i32 m0, s16, 0x2000
	v_cmp_lt_i32_e32 vcc, 3, v15
	global_load_lds_dwordx4 v[4:5], off
	s_mov_b32 m0, s10
	s_nop 0
	global_load_lds_dwordx4 v[116:117], off
	s_add_i32 m0, s16, 0xa000
	s_nop 0
	global_load_lds_dwordx4 v[120:121], off
	s_add_i32 m0, s16, 0xc000
	s_nop 0
	global_load_lds_dwordx4 v[124:125], off
	s_waitcnt vmcnt(0)
	s_waitcnt vmcnt(0) lgkmcnt(0)
	s_barrier
	s_and_saveexec_b64 s[10:11], vcc
	s_cbranch_execz .Lprio_skip_2
	s_setprio 1
